# F1 merge epilogue: progressive counted vmcnt waits on the late gate loads instead of a full drain (on top of v096)
# baseline (speedup 1.0000x reference)
.LBB0_161:
	s_waitcnt vmcnt(7)
	v_lshlrev_b32_e32 v178, 16, v174
	v_and_b32_e32 v179, 0xffff0000, v174
	v_pk_fma_f32 v[142:143], v[60:61], v[178:179], v[142:143]
	v_lshlrev_b32_e32 v60, 16, v175
	v_and_b32_e32 v61, 0xffff0000, v175
	v_pk_fma_f32 v[144:145], v[62:63], v[60:61], v[144:145]
	v_lshlrev_b32_e32 v60, 16, v176
	v_and_b32_e32 v61, 0xffff0000, v176
	v_pk_fma_f32 v[138:139], v[56:57], v[60:61], v[138:139]
	v_lshlrev_b32_e32 v56, 16, v177
	v_and_b32_e32 v57, 0xffff0000, v177
	v_pk_fma_f32 v[140:141], v[58:59], v[56:57], v[140:141]
	s_waitcnt vmcnt(6)
	v_lshlrev_b32_e32 v56, 16, v170
	v_and_b32_e32 v57, 0xffff0000, v170
	v_pk_fma_f32 v[134:135], v[52:53], v[56:57], v[134:135]
	v_lshlrev_b32_e32 v52, 16, v171
	v_and_b32_e32 v53, 0xffff0000, v171
	v_pk_fma_f32 v[136:137], v[54:55], v[52:53], v[136:137]
	v_lshlrev_b32_e32 v52, 16, v172
	v_and_b32_e32 v53, 0xffff0000, v172
	v_pk_fma_f32 v[130:131], v[48:49], v[52:53], v[130:131]
	v_lshlrev_b32_e32 v48, 16, v173
	v_and_b32_e32 v49, 0xffff0000, v173
	v_pk_fma_f32 v[132:133], v[50:51], v[48:49], v[132:133]
	s_waitcnt vmcnt(5)
	v_lshlrev_b32_e32 v48, 16, v166
	v_and_b32_e32 v49, 0xffff0000, v166
	v_pk_fma_f32 v[122:123], v[44:45], v[48:49], v[122:123]
	v_lshlrev_b32_e32 v44, 16, v167
	v_and_b32_e32 v45, 0xffff0000, v167
	v_pk_fma_f32 v[124:125], v[46:47], v[44:45], v[124:125]
	v_lshlrev_b32_e32 v44, 16, v168
	v_and_b32_e32 v45, 0xffff0000, v168
	v_pk_fma_f32 v[98:99], v[40:41], v[44:45], v[98:99]
	v_lshlrev_b32_e32 v40, 16, v169
	v_and_b32_e32 v41, 0xffff0000, v169
	v_pk_fma_f32 v[102:103], v[42:43], v[40:41], v[102:103]
	s_waitcnt vmcnt(4)
	v_lshlrev_b32_e32 v40, 16, v162
	v_and_b32_e32 v41, 0xffff0000, v162
	v_pk_fma_f32 v[78:79], v[36:37], v[40:41], v[78:79]
	v_lshlrev_b32_e32 v36, 16, v163
	v_and_b32_e32 v37, 0xffff0000, v163
	v_pk_fma_f32 v[80:81], v[38:39], v[36:37], v[80:81]
	v_lshlrev_b32_e32 v36, 16, v164
	v_and_b32_e32 v37, 0xffff0000, v164
	v_pk_fma_f32 v[72:73], v[32:33], v[36:37], v[72:73]
	v_lshlrev_b32_e32 v32, 16, v165
	v_and_b32_e32 v33, 0xffff0000, v165
	v_pk_fma_f32 v[74:75], v[34:35], v[32:33], v[74:75]
	s_waitcnt vmcnt(3)
	v_lshlrev_b32_e32 v32, 16, v158
	v_and_b32_e32 v33, 0xffff0000, v158
	v_pk_fma_f32 v[118:119], v[28:29], v[32:33], v[118:119]
	v_lshlrev_b32_e32 v28, 16, v159
	v_and_b32_e32 v29, 0xffff0000, v159
	v_pk_fma_f32 v[120:121], v[30:31], v[28:29], v[120:121]
	v_lshlrev_b32_e32 v28, 16, v160
	v_and_b32_e32 v29, 0xffff0000, v160
	v_pk_fma_f32 v[110:111], v[24:25], v[28:29], v[110:111]
	v_lshlrev_b32_e32 v24, 16, v161
	v_and_b32_e32 v25, 0xffff0000, v161
	v_pk_fma_f32 v[116:117], v[26:27], v[24:25], v[116:117]
	s_waitcnt vmcnt(2)
	v_lshlrev_b32_e32 v24, 16, v154
	v_and_b32_e32 v25, 0xffff0000, v154
	v_pk_fma_f32 v[106:107], v[20:21], v[24:25], v[106:107]
	v_lshlrev_b32_e32 v20, 16, v155
	v_and_b32_e32 v21, 0xffff0000, v155
	v_pk_fma_f32 v[112:113], v[22:23], v[20:21], v[112:113]
	v_lshlrev_b32_e32 v20, 16, v156
	v_and_b32_e32 v21, 0xffff0000, v156
	v_pk_fma_f32 v[104:105], v[16:17], v[20:21], v[104:105]
	v_lshlrev_b32_e32 v16, 16, v157
	v_and_b32_e32 v17, 0xffff0000, v157
	v_pk_fma_f32 v[108:109], v[18:19], v[16:17], v[108:109]
	s_waitcnt vmcnt(1)
	v_lshlrev_b32_e32 v16, 16, v150
	v_and_b32_e32 v17, 0xffff0000, v150
	v_pk_fma_f32 v[96:97], v[12:13], v[16:17], v[96:97]
	v_lshlrev_b32_e32 v12, 16, v151
	v_and_b32_e32 v13, 0xffff0000, v151
	v_pk_fma_f32 v[100:101], v[14:15], v[12:13], v[100:101]
	v_lshlrev_b32_e32 v12, 16, v152
	v_and_b32_e32 v13, 0xffff0000, v152
	v_pk_fma_f32 v[88:89], v[8:9], v[12:13], v[88:89]
	v_lshlrev_b32_e32 v8, 16, v153
	v_and_b32_e32 v9, 0xffff0000, v153
	v_pk_fma_f32 v[92:93], v[10:11], v[8:9], v[92:93]
	s_waitcnt vmcnt(0)
	v_lshlrev_b32_e32 v8, 16, v146
	v_and_b32_e32 v9, 0xffff0000, v146
	v_pk_fma_f32 v[84:85], v[4:5], v[8:9], v[84:85]
	v_lshlrev_b32_e32 v4, 16, v147
	v_and_b32_e32 v5, 0xffff0000, v147
	v_pk_fma_f32 v[90:91], v[6:7], v[4:5], v[90:91]
	v_lshlrev_b32_e32 v4, 16, v148
	v_and_b32_e32 v5, 0xffff0000, v148
	v_pk_fma_f32 v[82:83], v[0:1], v[4:5], v[82:83]
	v_lshlrev_b32_e32 v0, 16, v149
	v_and_b32_e32 v1, 0xffff0000, v149
	s_add_i32 s11, s11, 1
	s_cmp_eq_u32 s11, 3
	v_pk_fma_f32 v[86:87], v[2:3], v[0:1], v[86:87]
	s_cbranch_scc1 .LBB0_159
